# adds 64-bit accumulator zeroing placed before the deferred restore barrier
# speedup vs baseline: 1.0038x; 1.0011x over previous
; #define PG8_BAR __builtin_amdgcn_s_barrier()
; template <class Epi>
; __device__ __forceinline__ void gemm_phase(PG8_LAS unsigned char* lds, PG8_LAS unsigned char* xl, const Gemm g, const Sched& S, const Epi& E, const int wid) {
;     ...
;         for (int a = 0; a < 2; ++a)
; #pragma unroll
;             for (int b = 0; b < 2; ++b)
; #pragma unroll
;                 for (int m = 0; m < 4; ++m)
; #pragma unroll
;                     for (int n = 0; n < 2; ++n) acc[a][b][m][n] = (f32x4){0.f, 0.f, 0.f, 0.f};
;         cur = nxt; cA = nA; cB = nB; ++ui;
;         if (wr == 1) PG8_BAR;
.LBB0_219:
	s_ashr_i32 s21, s20, 31
	s_lshl_b64 s[8:9], s[20:21], 20
	s_add_u32 s30, s60, s8
	s_addc_u32 s31, s61, s9
	s_and_b64 s[8:9], s[40:41], exec
	s_cselect_b32 s8, s31, s51
	s_cselect_b32 s9, s30, s50
	s_ashr_i32 s13, s12, 31
	s_lshl_b64 s[10:11], s[12:13], 20
	s_add_u32 s48, s62, s10
	s_addc_u32 s49, s66, s11
	s_and_b64 s[10:11], s[40:41], exec
	s_cselect_b32 s10, s49, s53
	s_cselect_b32 s11, s48, s52
	s_add_u32 s13, s52, 0x100
	v_mov_b32_e32 v0, 0
	s_addc_u32 s21, s53, 0
	s_mov_b32 s43, -2
	v_mov_b32_e32 v1, v0
	v_mov_b64_e32 v[2:3], 0
	v_mov_b64_e32 v[4:5], 0
	v_mov_b64_e32 v[6:7], 0
	v_mov_b64_e32 v[8:9], 0
	v_mov_b64_e32 v[10:11], 0
	v_mov_b64_e32 v[12:13], 0
	v_mov_b64_e32 v[14:15], 0
	v_mov_b64_e32 v[16:17], 0
	v_mov_b64_e32 v[18:19], 0
	v_mov_b64_e32 v[20:21], 0
	v_mov_b64_e32 v[22:23], 0
	v_mov_b64_e32 v[24:25], 0
	v_mov_b64_e32 v[26:27], 0
	v_mov_b64_e32 v[28:29], 0
	v_mov_b64_e32 v[30:31], 0
	v_mov_b64_e32 v[32:33], 0
	v_mov_b64_e32 v[34:35], 0
	v_mov_b64_e32 v[36:37], 0
	v_mov_b64_e32 v[38:39], 0
	v_mov_b64_e32 v[40:41], 0
	v_mov_b64_e32 v[42:43], 0
	v_mov_b64_e32 v[44:45], 0
	v_mov_b64_e32 v[46:47], 0
	v_mov_b64_e32 v[48:49], 0
	v_mov_b64_e32 v[50:51], 0
	v_mov_b64_e32 v[52:53], 0
	v_mov_b64_e32 v[54:55], 0
	v_mov_b64_e32 v[56:57], 0
	v_mov_b64_e32 v[58:59], 0
	v_mov_b64_e32 v[60:61], 0
	v_mov_b64_e32 v[62:63], 0
	v_mov_b64_e32 v[64:65], 0
	v_mov_b64_e32 v[66:67], 0
	v_mov_b64_e32 v[68:69], 0
	v_mov_b64_e32 v[70:71], 0
	v_mov_b64_e32 v[72:73], 0
	v_mov_b64_e32 v[74:75], 0
	v_mov_b64_e32 v[76:77], 0
	v_mov_b64_e32 v[78:79], 0
	v_mov_b64_e32 v[80:81], 0
	v_mov_b64_e32 v[82:83], 0
	v_mov_b64_e32 v[84:85], 0
	v_mov_b64_e32 v[86:87], 0
	v_mov_b64_e32 v[88:89], 0
	v_mov_b64_e32 v[90:91], 0
	v_mov_b64_e32 v[92:93], 0
	v_mov_b64_e32 v[94:95], 0
	v_mov_b64_e32 v[96:97], 0
	v_mov_b64_e32 v[98:99], 0
	v_mov_b64_e32 v[100:101], 0
	v_mov_b64_e32 v[102:103], 0
	v_mov_b64_e32 v[104:105], 0
	v_mov_b64_e32 v[106:107], 0
	v_mov_b64_e32 v[108:109], 0
	v_mov_b64_e32 v[110:111], 0
	v_mov_b64_e32 v[112:113], 0
	v_mov_b64_e32 v[114:115], 0
	v_mov_b64_e32 v[116:117], 0
	v_mov_b64_e32 v[118:119], 0
	v_mov_b64_e32 v[120:121], 0
	v_mov_b64_e32 v[122:123], 0
	v_mov_b64_e32 v[124:125], 0
	v_mov_b64_e32 v[126:127], 0
	s_cmp_lg_u32 s100, 1
	s_cbranch_scc1 .Ldefbar_skip_0
	s_mov_b32 s100, 0
	s_barrier

; #define PG8_BAR __builtin_amdgcn_s_barrier()
; template <class Epi>
; __device__ __forceinline__ void gemm_phase(PG8_LAS unsigned char* lds, PG8_LAS unsigned char* xl, const Gemm g, const Sched& S, const Epi& E, const int wid) {
;     ...
;         for (int a = 0; a < 2; ++a)
; #pragma unroll
;             for (int b = 0; b < 2; ++b)
; #pragma unroll
;                 for (int m = 0; m < 4; ++m)
; #pragma unroll
;                     for (int n = 0; n < 2; ++n) acc[a][b][m][n] = (f32x4){0.f, 0.f, 0.f, 0.f};
;         cur = nxt; cA = nA; cB = nB; ++ui;
;         if (wr == 1) PG8_BAR;
.LBB0_237:
	s_ashr_i32 s59, s58, 31
	s_lshl_b64 s[8:9], s[58:59], 20
	s_add_u32 s36, s61, s8
	s_addc_u32 s37, s76, s9
	s_and_b64 s[8:9], s[40:41], exec
	s_cselect_b32 s8, s37, s21
	s_cselect_b32 s9, s36, s20
	s_ashr_i32 s57, s56, 31
	s_lshl_b64 s[10:11], s[56:57], 20
	s_add_u32 s52, s1, s10
	s_addc_u32 s53, s60, s11
	s_and_b64 s[10:11], s[40:41], exec
	s_cselect_b32 s10, s53, s31
	s_cselect_b32 s11, s52, s30
	s_add_u32 s13, s30, 0x100
	v_mov_b32_e32 v0, 0
	s_addc_u32 s57, s31, 0
	s_mov_b32 s62, -2
	v_mov_b32_e32 v1, v0
	s_waitcnt lgkmcnt(0)
	v_mov_b64_e32 v[2:3], 0
	v_mov_b64_e32 v[4:5], 0
	v_mov_b64_e32 v[6:7], 0
	v_mov_b64_e32 v[8:9], 0
	v_mov_b64_e32 v[10:11], 0
	v_mov_b64_e32 v[12:13], 0
	v_mov_b64_e32 v[14:15], 0
	v_mov_b64_e32 v[26:27], 0
	v_mov_b64_e32 v[28:29], 0
	v_mov_b64_e32 v[30:31], 0
	v_mov_b64_e32 v[32:33], 0
	v_mov_b64_e32 v[34:35], 0
	v_mov_b64_e32 v[36:37], 0
	v_mov_b64_e32 v[38:39], 0
	v_mov_b64_e32 v[40:41], 0
	v_mov_b64_e32 v[42:43], 0
	v_mov_b64_e32 v[44:45], 0
	v_mov_b64_e32 v[46:47], 0
	v_mov_b64_e32 v[48:49], 0
	v_mov_b64_e32 v[50:51], 0
	v_mov_b64_e32 v[52:53], 0
	v_mov_b64_e32 v[54:55], 0
	v_mov_b64_e32 v[56:57], 0
	v_mov_b64_e32 v[58:59], 0
	v_mov_b64_e32 v[60:61], 0
	v_mov_b64_e32 v[62:63], 0
	v_mov_b64_e32 v[64:65], 0
	v_mov_b64_e32 v[66:67], 0
	v_mov_b64_e32 v[68:69], 0
	v_mov_b64_e32 v[70:71], 0
	v_mov_b64_e32 v[72:73], 0
	v_mov_b64_e32 v[74:75], 0
	v_mov_b64_e32 v[76:77], 0
	v_mov_b64_e32 v[78:79], 0
	v_mov_b64_e32 v[80:81], 0
	v_mov_b64_e32 v[82:83], 0
	v_mov_b64_e32 v[84:85], 0
	v_mov_b64_e32 v[86:87], 0
	v_mov_b64_e32 v[88:89], 0
	v_mov_b64_e32 v[92:93], 0
	v_mov_b64_e32 v[94:95], 0
	v_mov_b64_e32 v[96:97], 0
	v_mov_b64_e32 v[98:99], 0
	v_mov_b64_e32 v[100:101], 0
	v_mov_b64_e32 v[102:103], 0
	v_mov_b64_e32 v[104:105], 0
	v_mov_b64_e32 v[106:107], 0
	v_mov_b64_e32 v[108:109], 0
	v_mov_b64_e32 v[110:111], 0
	v_mov_b64_e32 v[112:113], 0
	v_mov_b64_e32 v[114:115], 0
	v_mov_b64_e32 v[116:117], 0
	v_mov_b64_e32 v[118:119], 0
	v_mov_b64_e32 v[120:121], 0
	v_mov_b64_e32 v[122:123], 0
	v_mov_b64_e32 v[124:125], 0
	v_mov_b64_e32 v[126:127], 0
	v_mov_b64_e32 v[128:129], 0
	v_mov_b64_e32 v[130:131], 0
	v_mov_b64_e32 v[132:133], 0
	v_mov_b64_e32 v[134:135], 0
	v_mov_b64_e32 v[136:137], 0
	v_mov_b64_e32 v[138:139], 0
	s_cmp_lg_u32 s100, 1
	s_cbranch_scc1 .Ldefbar_skip_1
	s_mov_b32 s100, 0
	s_barrier

; #define PG8_BAR __builtin_amdgcn_s_barrier()
; template <class Epi>
; __device__ __forceinline__ void gemm_phase(PG8_LAS unsigned char* lds, PG8_LAS unsigned char* xl, const Gemm g, const Sched& S, const Epi& E, const int wid) {
;     ...
;         for (int a = 0; a < 2; ++a)
; #pragma unroll
;             for (int b = 0; b < 2; ++b)
; #pragma unroll
;                 for (int m = 0; m < 4; ++m)
; #pragma unroll
;                     for (int n = 0; n < 2; ++n) acc[a][b][m][n] = (f32x4){0.f, 0.f, 0.f, 0.f};
;         cur = nxt; cA = nA; cB = nB; ++ui;
;         if (wr == 1) PG8_BAR;
.LBB0_407:
	s_add_u32 s8, s76, 0x100
	v_mov_b32_e32 v0, 0
	s_addc_u32 s9, s77, 0
	s_mov_b32 s10, -2
	v_mov_b32_e32 v1, v0
	v_mov_b64_e32 v[2:3], 0
	v_mov_b64_e32 v[4:5], 0
	v_mov_b64_e32 v[6:7], 0
	v_mov_b64_e32 v[8:9], 0
	v_mov_b64_e32 v[10:11], 0
	v_mov_b64_e32 v[12:13], 0
	v_mov_b64_e32 v[14:15], 0
	v_mov_b64_e32 v[16:17], 0
	v_mov_b64_e32 v[18:19], 0
	v_mov_b64_e32 v[20:21], 0
	v_mov_b64_e32 v[22:23], 0
	v_mov_b64_e32 v[24:25], 0
	v_mov_b64_e32 v[26:27], 0
	v_mov_b64_e32 v[28:29], 0
	v_mov_b64_e32 v[30:31], 0
	v_mov_b64_e32 v[32:33], 0
	v_mov_b64_e32 v[34:35], 0
	v_mov_b64_e32 v[36:37], 0
	v_mov_b64_e32 v[38:39], 0
	v_mov_b64_e32 v[40:41], 0
	v_mov_b64_e32 v[42:43], 0
	v_mov_b64_e32 v[44:45], 0
	v_mov_b64_e32 v[46:47], 0
	v_mov_b64_e32 v[48:49], 0
	v_mov_b64_e32 v[50:51], 0
	v_mov_b64_e32 v[52:53], 0
	v_mov_b64_e32 v[54:55], 0
	v_mov_b64_e32 v[56:57], 0
	v_mov_b64_e32 v[58:59], 0
	v_mov_b64_e32 v[60:61], 0
	v_mov_b64_e32 v[62:63], 0
	v_mov_b64_e32 v[64:65], 0
	v_mov_b64_e32 v[66:67], 0
	v_mov_b64_e32 v[68:69], 0
	v_mov_b64_e32 v[70:71], 0
	v_mov_b64_e32 v[72:73], 0
	v_mov_b64_e32 v[74:75], 0
	v_mov_b64_e32 v[76:77], 0
	v_mov_b64_e32 v[78:79], 0
	v_mov_b64_e32 v[80:81], 0
	v_mov_b64_e32 v[82:83], 0
	v_mov_b64_e32 v[84:85], 0
	v_mov_b64_e32 v[86:87], 0
	v_mov_b64_e32 v[88:89], 0
	v_mov_b64_e32 v[90:91], 0
	v_mov_b64_e32 v[92:93], 0
	v_mov_b64_e32 v[94:95], 0
	v_mov_b64_e32 v[96:97], 0
	v_mov_b64_e32 v[98:99], 0
	v_mov_b64_e32 v[100:101], 0
	v_mov_b64_e32 v[102:103], 0
	v_mov_b64_e32 v[104:105], 0
	v_mov_b64_e32 v[106:107], 0
	v_mov_b64_e32 v[108:109], 0
	v_mov_b64_e32 v[110:111], 0
	v_mov_b64_e32 v[112:113], 0
	v_mov_b64_e32 v[114:115], 0
	v_mov_b64_e32 v[116:117], 0
	v_mov_b64_e32 v[118:119], 0
	v_mov_b64_e32 v[120:121], 0
	v_mov_b64_e32 v[122:123], 0
	v_mov_b64_e32 v[124:125], 0
	v_mov_b64_e32 v[126:127], 0
	s_cmp_lg_u32 s100, 1
	s_cbranch_scc1 .Ldefbar_skip_2
	s_mov_b32 s100, 0
	s_barrier

; #define PG8_BAR __builtin_amdgcn_s_barrier()
; template <class Epi>
; __device__ __forceinline__ void gemm_phase(PG8_LAS unsigned char* lds, PG8_LAS unsigned char* xl, const Gemm g, const Sched& S, const Epi& E, const int wid) {
;     ...
;         for (int a = 0; a < 2; ++a)
; #pragma unroll
;             for (int b = 0; b < 2; ++b)
; #pragma unroll
;                 for (int m = 0; m < 4; ++m)
; #pragma unroll
;                     for (int n = 0; n < 2; ++n) acc[a][b][m][n] = (f32x4){0.f, 0.f, 0.f, 0.f};
;         cur = nxt; cA = nA; cB = nB; ++ui;
;         if (wr == 1) PG8_BAR;
.LBB0_427:
	s_add_u32 s8, s60, 0x100
	v_mov_b32_e32 v0, 0
	s_addc_u32 s9, s61, 0
	s_mov_b32 s10, -2
	v_mov_b32_e32 v1, v0
	v_mov_b64_e32 v[2:3], 0
	v_mov_b64_e32 v[4:5], 0
	v_mov_b64_e32 v[6:7], 0
	v_mov_b64_e32 v[8:9], 0
	v_mov_b64_e32 v[10:11], 0
	v_mov_b64_e32 v[12:13], 0
	v_mov_b64_e32 v[14:15], 0
	v_mov_b64_e32 v[16:17], 0
	v_mov_b64_e32 v[18:19], 0
	v_mov_b64_e32 v[20:21], 0
	v_mov_b64_e32 v[22:23], 0
	v_mov_b64_e32 v[24:25], 0
	v_mov_b64_e32 v[26:27], 0
	v_mov_b64_e32 v[28:29], 0
	v_mov_b64_e32 v[30:31], 0
	v_mov_b64_e32 v[32:33], 0
	v_mov_b64_e32 v[34:35], 0
	v_mov_b64_e32 v[36:37], 0
	v_mov_b64_e32 v[38:39], 0
	v_mov_b64_e32 v[40:41], 0
	v_mov_b64_e32 v[42:43], 0
	v_mov_b64_e32 v[44:45], 0
	v_mov_b64_e32 v[46:47], 0
	v_mov_b64_e32 v[48:49], 0
	v_mov_b64_e32 v[50:51], 0
	v_mov_b64_e32 v[52:53], 0
	v_mov_b64_e32 v[54:55], 0
	v_mov_b64_e32 v[56:57], 0
	v_mov_b64_e32 v[58:59], 0
	v_mov_b64_e32 v[60:61], 0
	v_mov_b64_e32 v[62:63], 0
	v_mov_b64_e32 v[64:65], 0
	v_mov_b64_e32 v[66:67], 0
	v_mov_b64_e32 v[68:69], 0
	v_mov_b64_e32 v[70:71], 0
	v_mov_b64_e32 v[72:73], 0
	v_mov_b64_e32 v[74:75], 0
	v_mov_b64_e32 v[76:77], 0
	v_mov_b64_e32 v[78:79], 0
	v_mov_b64_e32 v[80:81], 0
	v_mov_b64_e32 v[82:83], 0
	v_mov_b64_e32 v[84:85], 0
	v_mov_b64_e32 v[86:87], 0
	v_mov_b64_e32 v[88:89], 0
	v_mov_b64_e32 v[90:91], 0
	v_mov_b64_e32 v[92:93], 0
	v_mov_b64_e32 v[94:95], 0
	v_mov_b64_e32 v[96:97], 0
	v_mov_b64_e32 v[98:99], 0
	v_mov_b64_e32 v[100:101], 0
	v_mov_b64_e32 v[102:103], 0
	v_mov_b64_e32 v[104:105], 0
	v_mov_b64_e32 v[106:107], 0
	v_mov_b64_e32 v[108:109], 0
	v_mov_b64_e32 v[110:111], 0
	v_mov_b64_e32 v[112:113], 0
	v_mov_b64_e32 v[114:115], 0
	v_mov_b64_e32 v[116:117], 0
	v_mov_b64_e32 v[118:119], 0
	v_mov_b64_e32 v[120:121], 0
	v_mov_b64_e32 v[122:123], 0
	v_mov_b64_e32 v[124:125], 0
	v_mov_b64_e32 v[126:127], 0
	s_cmp_lg_u32 s100, 1
	s_cbranch_scc1 .Ldefbar_skip_3
	s_mov_b32 s100, 0
	s_barrier

; #define PG8_BAR __builtin_amdgcn_s_barrier()
; template <class Epi>
; __device__ __forceinline__ void gemm_phase(PG8_LAS unsigned char* lds, PG8_LAS unsigned char* xl, const Gemm g, const Sched& S, const Epi& E, const int wid) {
;     ...
;         for (int a = 0; a < 2; ++a)
; #pragma unroll
;             for (int b = 0; b < 2; ++b)
; #pragma unroll
;                 for (int m = 0; m < 4; ++m)
; #pragma unroll
;                     for (int n = 0; n < 2; ++n) acc[a][b][m][n] = (f32x4){0.f, 0.f, 0.f, 0.f};
;         cur = nxt; cA = nA; cB = nB; ++ui;
;         if (wr == 1) PG8_BAR;
.LBB0_526:
	s_ashr_i32 s37, s36, 31
	s_lshl_b64 s[8:9], s[36:37], 20
	s_add_u32 s42, s76, s8
	s_addc_u32 s43, s77, s9
	s_and_b64 s[8:9], s[46:47], exec
	s_cselect_b32 s8, s43, s13
	s_cselect_b32 s9, s42, s12
	s_ashr_i32 s59, s58, 31
	s_lshl_b64 s[10:11], s[58:59], 20
	s_add_u32 s30, s60, s10
	s_addc_u32 s31, s61, s11
	s_and_b64 s[10:11], s[46:47], exec
	s_cselect_b32 s10, s31, s21
	s_cselect_b32 s11, s30, s20
	s_add_u32 s59, s20, 0x100
	v_mov_b32_e32 v0, 0
	s_addc_u32 s62, s21, 0
	s_mov_b32 s66, -2
	v_mov_b32_e32 v1, v0
	s_waitcnt lgkmcnt(0)
	v_mov_b64_e32 v[2:3], 0
	v_mov_b64_e32 v[4:5], 0
	v_mov_b64_e32 v[6:7], 0
	v_mov_b64_e32 v[8:9], 0
	v_mov_b64_e32 v[10:11], 0
	v_mov_b64_e32 v[12:13], 0
	v_mov_b64_e32 v[14:15], 0
	v_mov_b64_e32 v[18:19], 0
	v_mov_b64_e32 v[20:21], 0
	v_mov_b64_e32 v[30:31], 0
	v_mov_b64_e32 v[32:33], 0
	v_mov_b64_e32 v[34:35], 0
	v_mov_b64_e32 v[36:37], 0
	v_mov_b64_e32 v[38:39], 0
	v_mov_b64_e32 v[40:41], 0
	v_mov_b64_e32 v[42:43], 0
	v_mov_b64_e32 v[44:45], 0
	v_mov_b64_e32 v[46:47], 0
	v_mov_b64_e32 v[48:49], 0
	v_mov_b64_e32 v[50:51], 0
	v_mov_b64_e32 v[52:53], 0
	v_mov_b64_e32 v[54:55], 0
	v_mov_b64_e32 v[56:57], 0
	v_mov_b64_e32 v[58:59], 0
	v_mov_b64_e32 v[60:61], 0
	v_mov_b64_e32 v[62:63], 0
	v_mov_b64_e32 v[64:65], 0
	v_mov_b64_e32 v[66:67], 0
	v_mov_b64_e32 v[68:69], 0
	v_mov_b64_e32 v[70:71], 0
	v_mov_b64_e32 v[72:73], 0
	v_mov_b64_e32 v[74:75], 0
	v_mov_b64_e32 v[76:77], 0
	v_mov_b64_e32 v[78:79], 0
	v_mov_b64_e32 v[80:81], 0
	v_mov_b64_e32 v[82:83], 0
	v_mov_b64_e32 v[84:85], 0
	v_mov_b64_e32 v[86:87], 0
	v_mov_b64_e32 v[88:89], 0
	v_mov_b64_e32 v[92:93], 0
	v_mov_b64_e32 v[94:95], 0
	v_mov_b64_e32 v[96:97], 0
	v_mov_b64_e32 v[98:99], 0
	v_mov_b64_e32 v[100:101], 0
	v_mov_b64_e32 v[102:103], 0
	v_mov_b64_e32 v[104:105], 0
	v_mov_b64_e32 v[106:107], 0
	v_mov_b64_e32 v[108:109], 0
	v_mov_b64_e32 v[110:111], 0
	v_mov_b64_e32 v[112:113], 0
	v_mov_b64_e32 v[114:115], 0
	v_mov_b64_e32 v[116:117], 0
	v_mov_b64_e32 v[118:119], 0
	v_mov_b64_e32 v[120:121], 0
	v_mov_b64_e32 v[122:123], 0
	v_mov_b64_e32 v[124:125], 0
	v_mov_b64_e32 v[126:127], 0
	v_mov_b64_e32 v[128:129], 0
	v_mov_b64_e32 v[130:131], 0
	v_mov_b64_e32 v[132:133], 0
	v_mov_b64_e32 v[134:135], 0
	v_mov_b64_e32 v[136:137], 0
	v_mov_b64_e32 v[138:139], 0
	s_cmp_lg_u32 s100, 1
	s_cbranch_scc1 .Ldefbar_skip_4
	s_mov_b32 s100, 0
	s_barrier

; #define PG8_BAR __builtin_amdgcn_s_barrier()
; template <class Epi>
; __device__ __forceinline__ void gemm_phase(PG8_LAS unsigned char* lds, PG8_LAS unsigned char* xl, const Gemm g, const Sched& S, const Epi& E, const int wid) {
;     ...
;         for (int a = 0; a < 2; ++a)
; #pragma unroll
;             for (int b = 0; b < 2; ++b)
; #pragma unroll
;                 for (int m = 0; m < 4; ++m)
; #pragma unroll
;                     for (int n = 0; n < 2; ++n) acc[a][b][m][n] = (f32x4){0.f, 0.f, 0.f, 0.f};
;         cur = nxt; cA = nA; cB = nB; ++ui;
;         if (wr == 1) PG8_BAR;
.LBB0_688:
	s_ashr_i32 s13, s12, 31
	s_lshl_b64 s[10:11], s[12:13], 20
	s_add_u32 s30, s9, s10
	s_addc_u32 s31, s52, s11
	s_and_b64 s[10:11], s[48:49], exec
	s_cselect_b32 s10, s31, s45
	s_cselect_b32 s11, s30, s44
	s_lshl_b32 s40, s40, 8
	s_ashr_i32 s41, s40, 31
	s_lshl_b64 s[42:43], s[40:41], 1
	s_add_u32 s13, s59, s42
	s_addc_u32 s43, s60, s43
	s_mul_i32 s42, s66, 0x580000
	s_mul_hi_i32 s48, s66, 0x580000
	s_add_u32 s42, s13, s42
	s_addc_u32 s43, s43, s48
	s_add_u32 s48, s36, 0x2c0080
	s_addc_u32 s49, s37, 0
	s_add_u32 s13, s44, 0x100
	v_mov_b32_e32 v0, 0
	v_lshl_add_u64 v[136:137], s[48:49], 0, v[160:161]
	v_lshl_add_u64 v[138:139], s[48:49], 0, v[162:163]
	s_addc_u32 s67, s45, 0
	s_mov_b32 s70, -2
	s_mov_b64 s[44:45], 0
	v_mov_b32_e32 v1, v0
	v_mov_b64_e32 v[2:3], 0
	v_mov_b64_e32 v[4:5], 0
	v_mov_b64_e32 v[6:7], 0
	v_mov_b64_e32 v[8:9], 0
	v_mov_b64_e32 v[10:11], 0
	v_mov_b64_e32 v[12:13], 0
	v_mov_b64_e32 v[14:15], 0
	v_mov_b64_e32 v[16:17], 0
	v_mov_b64_e32 v[18:19], 0
	v_mov_b64_e32 v[20:21], 0
	v_mov_b64_e32 v[22:23], 0
	v_mov_b64_e32 v[24:25], 0
	v_mov_b64_e32 v[26:27], 0
	v_mov_b64_e32 v[28:29], 0
	v_mov_b64_e32 v[30:31], 0
	v_mov_b64_e32 v[32:33], 0
	v_mov_b64_e32 v[34:35], 0
	v_mov_b64_e32 v[36:37], 0
	v_mov_b64_e32 v[38:39], 0
	v_mov_b64_e32 v[40:41], 0
	v_mov_b64_e32 v[42:43], 0
	v_mov_b64_e32 v[44:45], 0
	v_mov_b64_e32 v[46:47], 0
	v_mov_b64_e32 v[48:49], 0
	v_mov_b64_e32 v[50:51], 0
	v_mov_b64_e32 v[52:53], 0
	v_mov_b64_e32 v[54:55], 0
	v_mov_b64_e32 v[56:57], 0
	v_mov_b64_e32 v[58:59], 0
	v_mov_b64_e32 v[60:61], 0
	v_mov_b64_e32 v[62:63], 0
	v_mov_b64_e32 v[64:65], 0
	v_mov_b64_e32 v[66:67], 0
	v_mov_b64_e32 v[68:69], 0
	v_mov_b64_e32 v[70:71], 0
	v_mov_b64_e32 v[72:73], 0
	v_mov_b64_e32 v[74:75], 0
	v_mov_b64_e32 v[76:77], 0
	v_mov_b64_e32 v[78:79], 0
	v_mov_b64_e32 v[80:81], 0
	v_mov_b64_e32 v[82:83], 0
	v_mov_b64_e32 v[84:85], 0
	v_mov_b64_e32 v[86:87], 0
	v_mov_b64_e32 v[88:89], 0
	v_mov_b64_e32 v[90:91], 0
	v_mov_b64_e32 v[92:93], 0
	v_mov_b64_e32 v[94:95], 0
	v_mov_b64_e32 v[96:97], 0
	v_mov_b64_e32 v[98:99], 0
	v_mov_b64_e32 v[100:101], 0
	v_mov_b64_e32 v[102:103], 0
	v_mov_b64_e32 v[104:105], 0
	v_mov_b64_e32 v[106:107], 0
	v_mov_b64_e32 v[108:109], 0
	v_mov_b64_e32 v[110:111], 0
	v_mov_b64_e32 v[112:113], 0
	v_mov_b64_e32 v[114:115], 0
	v_mov_b64_e32 v[116:117], 0
	v_mov_b64_e32 v[118:119], 0
	v_mov_b64_e32 v[120:121], 0
	v_mov_b64_e32 v[122:123], 0
	v_mov_b64_e32 v[124:125], 0
	v_mov_b64_e32 v[126:127], 0
	s_cmp_lg_u32 s100, 1
	s_cbranch_scc1 .Ldefbar_skip_5
	s_mov_b32 s100, 0
	s_barrier

; #define PG8_BAR __builtin_amdgcn_s_barrier()
; template <class Epi>
; __device__ __forceinline__ void gemm_phase(PG8_LAS unsigned char* lds, PG8_LAS unsigned char* xl, const Gemm g, const Sched& S, const Epi& E, const int wid) {
;     ...
;         for (int a = 0; a < 2; ++a)
; #pragma unroll
;             for (int b = 0; b < 2; ++b)
; #pragma unroll
;                 for (int m = 0; m < 4; ++m)
; #pragma unroll
;                     for (int n = 0; n < 2; ++n) acc[a][b][m][n] = (f32x4){0.f, 0.f, 0.f, 0.f};
;         cur = nxt; cA = nA; cB = nB; ++ui;
;         if (wr == 1) PG8_BAR;
.LBB0_764:
	s_ashr_i32 s31, s30, 31
	s_lshl_b64 s[8:9], s[30:31], 20
	s_add_u32 s40, s51, s8
	s_addc_u32 s41, s52, s9
	s_and_b64 s[8:9], s[48:49], exec
	s_cselect_b32 s8, s41, s45
	s_cselect_b32 s9, s40, s44
	s_add_u32 s42, s42, 0x2c0080
	s_addc_u32 s43, s43, 0
	s_add_u32 s10, s44, 0x100
	v_mov_b32_e32 v0, 0
	s_addc_u32 s11, s45, 0
	s_mov_b32 s13, -2
	s_waitcnt lgkmcnt(0)
	v_mov_b32_e32 v1, v0
	v_mov_b64_e32 v[2:3], 0
	v_mov_b64_e32 v[4:5], 0
	v_mov_b64_e32 v[6:7], 0
	v_mov_b64_e32 v[8:9], 0
	v_mov_b64_e32 v[10:11], 0
	v_mov_b64_e32 v[12:13], 0
	v_mov_b64_e32 v[14:15], 0
	v_mov_b64_e32 v[16:17], 0
	v_mov_b64_e32 v[18:19], 0
	v_mov_b64_e32 v[20:21], 0
	v_mov_b64_e32 v[22:23], 0
	v_mov_b64_e32 v[24:25], 0
	v_mov_b64_e32 v[26:27], 0
	v_mov_b64_e32 v[28:29], 0
	v_mov_b64_e32 v[30:31], 0
	v_mov_b64_e32 v[32:33], 0
	v_mov_b64_e32 v[34:35], 0
	v_mov_b64_e32 v[36:37], 0
	v_mov_b64_e32 v[38:39], 0
	v_mov_b64_e32 v[40:41], 0
	v_mov_b64_e32 v[42:43], 0
	v_mov_b64_e32 v[44:45], 0
	v_mov_b64_e32 v[46:47], 0
	v_mov_b64_e32 v[48:49], 0
	v_mov_b64_e32 v[50:51], 0
	v_mov_b64_e32 v[52:53], 0
	v_mov_b64_e32 v[54:55], 0
	v_mov_b64_e32 v[56:57], 0
	v_mov_b64_e32 v[58:59], 0
	v_mov_b64_e32 v[60:61], 0
	v_mov_b64_e32 v[62:63], 0
	v_mov_b64_e32 v[64:65], 0
	v_mov_b64_e32 v[66:67], 0
	v_mov_b64_e32 v[68:69], 0
	v_mov_b64_e32 v[70:71], 0
	v_mov_b64_e32 v[72:73], 0
	v_mov_b64_e32 v[74:75], 0
	v_mov_b64_e32 v[76:77], 0
	v_mov_b64_e32 v[78:79], 0
	v_mov_b64_e32 v[80:81], 0
	v_mov_b64_e32 v[82:83], 0
	v_mov_b64_e32 v[84:85], 0
	v_mov_b64_e32 v[86:87], 0
	v_mov_b64_e32 v[88:89], 0
	v_mov_b64_e32 v[90:91], 0
	v_mov_b64_e32 v[92:93], 0
	v_mov_b64_e32 v[94:95], 0
	v_mov_b64_e32 v[96:97], 0
	v_mov_b64_e32 v[98:99], 0
	v_mov_b64_e32 v[100:101], 0
	v_mov_b64_e32 v[102:103], 0
	v_mov_b64_e32 v[104:105], 0
	v_mov_b64_e32 v[106:107], 0
	v_mov_b64_e32 v[108:109], 0
	v_mov_b64_e32 v[110:111], 0
	v_mov_b64_e32 v[112:113], 0
	v_mov_b64_e32 v[114:115], 0
	v_mov_b64_e32 v[116:117], 0
	v_mov_b64_e32 v[118:119], 0
	v_mov_b64_e32 v[132:133], 0
	v_mov_b64_e32 v[134:135], 0
	v_mov_b64_e32 v[140:141], 0
	v_mov_b64_e32 v[142:143], 0
	s_cmp_lg_u32 s100, 1
	s_cbranch_scc1 .Ldefbar_skip_6
	s_mov_b32 s100, 0
	s_barrier

; #define PG8_BAR __builtin_amdgcn_s_barrier()
; template <class Epi>
; __device__ __forceinline__ void gemm_phase(PG8_LAS unsigned char* lds, PG8_LAS unsigned char* xl, const Gemm g, const Sched& S, const Epi& E, const int wid) {
;     ...
;         for (int a = 0; a < 2; ++a)
; #pragma unroll
;             for (int b = 0; b < 2; ++b)
; #pragma unroll
;                 for (int m = 0; m < 4; ++m)
; #pragma unroll
;                     for (int n = 0; n < 2; ++n) acc[a][b][m][n] = (f32x4){0.f, 0.f, 0.f, 0.f};
;         cur = nxt; cA = nA; cB = nB; ++ui;
;         if (wr == 1) PG8_BAR;
.LBB0_858:
	s_add_u32 s8, s50, 0x100
	v_mov_b32_e32 v0, 0
	s_addc_u32 s9, s51, 0
	s_mov_b32 s10, -2
	v_mov_b32_e32 v1, v0
	v_mov_b64_e32 v[2:3], 0
	v_mov_b64_e32 v[4:5], 0
	v_mov_b64_e32 v[6:7], 0
	v_mov_b64_e32 v[8:9], 0
	v_mov_b64_e32 v[10:11], 0
	v_mov_b64_e32 v[12:13], 0
	v_mov_b64_e32 v[14:15], 0
	v_mov_b64_e32 v[16:17], 0
	v_mov_b64_e32 v[18:19], 0
	v_mov_b64_e32 v[20:21], 0
	v_mov_b64_e32 v[22:23], 0
	v_mov_b64_e32 v[24:25], 0
	v_mov_b64_e32 v[26:27], 0
	v_mov_b64_e32 v[28:29], 0
	v_mov_b64_e32 v[30:31], 0
	v_mov_b64_e32 v[32:33], 0
	v_mov_b64_e32 v[34:35], 0
	v_mov_b64_e32 v[36:37], 0
	v_mov_b64_e32 v[38:39], 0
	v_mov_b64_e32 v[40:41], 0
	v_mov_b64_e32 v[42:43], 0
	v_mov_b64_e32 v[44:45], 0
	v_mov_b64_e32 v[46:47], 0
	v_mov_b64_e32 v[48:49], 0
	v_mov_b64_e32 v[50:51], 0
	v_mov_b64_e32 v[52:53], 0
	v_mov_b64_e32 v[54:55], 0
	v_mov_b64_e32 v[56:57], 0
	v_mov_b64_e32 v[58:59], 0
	v_mov_b64_e32 v[60:61], 0
	v_mov_b64_e32 v[62:63], 0
	v_mov_b64_e32 v[64:65], 0
	v_mov_b64_e32 v[66:67], 0
	v_mov_b64_e32 v[68:69], 0
	v_mov_b64_e32 v[70:71], 0
	v_mov_b64_e32 v[72:73], 0
	v_mov_b64_e32 v[74:75], 0
	v_mov_b64_e32 v[76:77], 0
	v_mov_b64_e32 v[78:79], 0
	v_mov_b64_e32 v[80:81], 0
	v_mov_b64_e32 v[82:83], 0
	v_mov_b64_e32 v[84:85], 0
	v_mov_b64_e32 v[86:87], 0
	v_mov_b64_e32 v[88:89], 0
	v_mov_b64_e32 v[90:91], 0
	v_mov_b64_e32 v[92:93], 0
	v_mov_b64_e32 v[94:95], 0
	v_mov_b64_e32 v[96:97], 0
	v_mov_b64_e32 v[98:99], 0
	v_mov_b64_e32 v[100:101], 0
	v_mov_b64_e32 v[102:103], 0
	v_mov_b64_e32 v[104:105], 0
	v_mov_b64_e32 v[106:107], 0
	v_mov_b64_e32 v[108:109], 0
	v_mov_b64_e32 v[110:111], 0
	v_mov_b64_e32 v[112:113], 0
	v_mov_b64_e32 v[114:115], 0
	v_mov_b64_e32 v[116:117], 0
	v_mov_b64_e32 v[118:119], 0
	v_mov_b64_e32 v[128:129], 0
	v_mov_b64_e32 v[130:131], 0
	v_mov_b64_e32 v[132:133], 0
	v_mov_b64_e32 v[134:135], 0
	s_cmp_lg_u32 s100, 1
	s_cbranch_scc1 .Ldefbar_skip_7
	s_mov_b32 s100, 0
	s_barrier

; #define PG8_BAR __builtin_amdgcn_s_barrier()
; template <class Epi>
; __device__ __forceinline__ void gemm_phase(PG8_LAS unsigned char* lds, PG8_LAS unsigned char* xl, const Gemm g, const Sched& S, const Epi& E, const int wid) {
;     ...
;         for (int a = 0; a < 2; ++a)
; #pragma unroll
;             for (int b = 0; b < 2; ++b)
; #pragma unroll
;                 for (int m = 0; m < 4; ++m)
; #pragma unroll
;                     for (int n = 0; n < 2; ++n) acc[a][b][m][n] = (f32x4){0.f, 0.f, 0.f, 0.f};
;         cur = nxt; cA = nA; cB = nB; ++ui;
;         if (wr == 1) PG8_BAR;
.LBB0_958:
	s_add_u32 s8, s56, 0x100
	v_mov_b32_e32 v0, 0
	s_addc_u32 s9, s57, 0
	s_mov_b32 s10, -2
	s_waitcnt lgkmcnt(0)
	v_mov_b32_e32 v1, v0
	v_mov_b64_e32 v[2:3], 0
	v_mov_b64_e32 v[4:5], 0
	v_mov_b64_e32 v[6:7], 0
	v_mov_b64_e32 v[8:9], 0
	v_mov_b64_e32 v[10:11], 0
	v_mov_b64_e32 v[12:13], 0
	v_mov_b64_e32 v[14:15], 0
	v_mov_b64_e32 v[16:17], 0
	v_mov_b64_e32 v[18:19], 0
	v_mov_b64_e32 v[20:21], 0
	v_mov_b64_e32 v[22:23], 0
	v_mov_b64_e32 v[24:25], 0
	v_mov_b64_e32 v[26:27], 0
	v_mov_b64_e32 v[28:29], 0
	v_mov_b64_e32 v[30:31], 0
	v_mov_b64_e32 v[32:33], 0
	v_mov_b64_e32 v[34:35], 0
	v_mov_b64_e32 v[36:37], 0
	v_mov_b64_e32 v[38:39], 0
	v_mov_b64_e32 v[40:41], 0
	v_mov_b64_e32 v[42:43], 0
	v_mov_b64_e32 v[44:45], 0
	v_mov_b64_e32 v[46:47], 0
	v_mov_b64_e32 v[48:49], 0
	v_mov_b64_e32 v[50:51], 0
	v_mov_b64_e32 v[52:53], 0
	v_mov_b64_e32 v[54:55], 0
	v_mov_b64_e32 v[56:57], 0
	v_mov_b64_e32 v[58:59], 0
	v_mov_b64_e32 v[60:61], 0
	v_mov_b64_e32 v[62:63], 0
	v_mov_b64_e32 v[64:65], 0
	v_mov_b64_e32 v[66:67], 0
	v_mov_b64_e32 v[68:69], 0
	v_mov_b64_e32 v[70:71], 0
	v_mov_b64_e32 v[72:73], 0
	v_mov_b64_e32 v[74:75], 0
	v_mov_b64_e32 v[76:77], 0
	v_mov_b64_e32 v[78:79], 0
	v_mov_b64_e32 v[80:81], 0
	v_mov_b64_e32 v[82:83], 0
	v_mov_b64_e32 v[84:85], 0
	v_mov_b64_e32 v[86:87], 0
	v_mov_b64_e32 v[88:89], 0
	v_mov_b64_e32 v[90:91], 0
	v_mov_b64_e32 v[92:93], 0
	v_mov_b64_e32 v[94:95], 0
	v_mov_b64_e32 v[96:97], 0
	v_mov_b64_e32 v[98:99], 0
	v_mov_b64_e32 v[100:101], 0
	v_mov_b64_e32 v[102:103], 0
	v_mov_b64_e32 v[104:105], 0
	v_mov_b64_e32 v[106:107], 0
	v_mov_b64_e32 v[108:109], 0
	v_mov_b64_e32 v[110:111], 0
	v_mov_b64_e32 v[112:113], 0
	v_mov_b64_e32 v[114:115], 0
	v_mov_b64_e32 v[116:117], 0
	v_mov_b64_e32 v[118:119], 0
	v_mov_b64_e32 v[120:121], 0
	v_mov_b64_e32 v[122:123], 0
	v_mov_b64_e32 v[132:133], 0
	v_mov_b64_e32 v[134:135], 0
	s_cmp_lg_u32 s100, 1
	s_cbranch_scc1 .Ldefbar_skip_8
	s_mov_b32 s100, 0
	s_barrier

; #define PG8_BAR __builtin_amdgcn_s_barrier()
; template <class Epi>
; __device__ __forceinline__ void gemm_phase(PG8_LAS unsigned char* lds, PG8_LAS unsigned char* xl, const Gemm g, const Sched& S, const Epi& E, const int wid) {
;     ...
;         for (int a = 0; a < 2; ++a)
; #pragma unroll
;             for (int b = 0; b < 2; ++b)
; #pragma unroll
;                 for (int m = 0; m < 4; ++m)
; #pragma unroll
;                     for (int n = 0; n < 2; ++n) acc[a][b][m][n] = (f32x4){0.f, 0.f, 0.f, 0.f};
;         cur = nxt; cA = nA; cB = nB; ++ui;
;         if (wr == 1) PG8_BAR;
.LBB0_1105:
	s_ashr_i32 s51, s50, 31
	s_lshl_b64 s[8:9], s[50:51], 20
	s_add_u32 s56, s62, s8
	s_addc_u32 s57, s69, s9
	s_and_b64 s[8:9], s[46:47], exec
	s_cselect_b32 s8, s57, s45
	s_cselect_b32 s9, s56, s44
	s_ashr_i32 s49, s48, 31
	s_lshl_b64 s[10:11], s[48:49], 20
	s_add_u32 s58, s88, s10
	s_addc_u32 s59, s89, s11
	s_and_b64 s[10:11], s[46:47], exec
	s_cselect_b32 s49, s59, s77
	s_cselect_b32 s61, s58, s76
	s_add_u32 s72, s76, 0x100
	v_mov_b32_e32 v64, 0
	s_addc_u32 s73, s77, 0
	s_mov_b32 s54, -2
	v_mov_b64_e32 v[12:13], 0
	v_mov_b64_e32 v[14:15], 0
	v_mov_b64_e32 v[16:17], 0
	v_mov_b64_e32 v[18:19], 0
	v_mov_b64_e32 v[20:21], 0
	v_mov_b64_e32 v[22:23], 0
	v_mov_b64_e32 v[24:25], 0
	v_mov_b64_e32 v[26:27], 0
	v_mov_b64_e32 v[28:29], 0
	v_mov_b64_e32 v[30:31], 0
	v_mov_b64_e32 v[32:33], 0
	v_mov_b64_e32 v[34:35], 0
	v_mov_b64_e32 v[36:37], 0
	v_mov_b64_e32 v[38:39], 0
	v_mov_b64_e32 v[40:41], 0
	v_mov_b64_e32 v[42:43], 0
	v_mov_b64_e32 v[44:45], 0
	v_mov_b64_e32 v[46:47], 0
	v_mov_b64_e32 v[48:49], 0
	v_mov_b64_e32 v[50:51], 0
	v_mov_b64_e32 v[52:53], 0
	v_mov_b64_e32 v[54:55], 0
	v_mov_b64_e32 v[56:57], 0
	v_mov_b64_e32 v[58:59], 0
	v_mov_b64_e32 v[60:61], 0
	v_mov_b64_e32 v[62:63], 0
	v_mov_b32_e32 v65, v64
	v_mov_b64_e32 v[66:67], 0
	v_mov_b64_e32 v[68:69], 0
	v_mov_b64_e32 v[70:71], 0
	v_mov_b64_e32 v[72:73], 0
	v_mov_b64_e32 v[74:75], 0
	v_mov_b64_e32 v[80:81], 0
	v_mov_b64_e32 v[82:83], 0
	v_mov_b64_e32 v[112:113], 0
	v_mov_b64_e32 v[114:115], 0
	v_mov_b64_e32 v[116:117], 0
	v_mov_b64_e32 v[118:119], 0
	v_mov_b64_e32 v[120:121], 0
	v_mov_b64_e32 v[122:123], 0
	v_mov_b64_e32 v[124:125], 0
	v_mov_b64_e32 v[126:127], 0
	v_mov_b64_e32 v[128:129], 0
	v_mov_b64_e32 v[130:131], 0
	v_mov_b64_e32 v[132:133], 0
	v_mov_b64_e32 v[134:135], 0
	v_mov_b64_e32 v[136:137], 0
	v_mov_b64_e32 v[138:139], 0
	v_mov_b64_e32 v[140:141], 0
	v_mov_b64_e32 v[142:143], 0
	v_mov_b64_e32 v[144:145], 0
	v_mov_b64_e32 v[146:147], 0
	v_mov_b64_e32 v[148:149], 0
	v_mov_b64_e32 v[150:151], 0
	v_mov_b64_e32 v[152:153], 0
	v_mov_b64_e32 v[154:155], 0
	v_mov_b64_e32 v[156:157], 0
	v_mov_b64_e32 v[158:159], 0
	v_mov_b64_e32 v[160:161], 0
	v_mov_b64_e32 v[162:163], 0
	v_mov_b64_e32 v[164:165], 0
	v_mov_b64_e32 v[166:167], 0
	v_mov_b64_e32 v[168:169], 0
	v_mov_b64_e32 v[170:171], 0
	s_cmp_lg_u32 s100, 1
	s_cbranch_scc1 .Ldefbar_skip_9
	s_mov_b32 s100, 0
	s_barrier

; #define PG8_BAR __builtin_amdgcn_s_barrier()
; template <class Epi>
; __device__ __forceinline__ void gemm_phase(PG8_LAS unsigned char* lds, PG8_LAS unsigned char* xl, const Gemm g, const Sched& S, const Epi& E, const int wid) {
;     ...
;         for (int a = 0; a < 2; ++a)
; #pragma unroll
;             for (int b = 0; b < 2; ++b)
; #pragma unroll
;                 for (int m = 0; m < 4; ++m)
; #pragma unroll
;                     for (int n = 0; n < 2; ++n) acc[a][b][m][n] = (f32x4){0.f, 0.f, 0.f, 0.f};
;         cur = nxt; cA = nA; cB = nB; ++ui;
;         if (wr == 1) PG8_BAR;
.LBB0_1303:
	s_add_u32 s36, s36, 0x160080
	s_addc_u32 s37, s37, 0
	s_add_u32 s1, s40, 0x100
	v_mov_b32_e32 v0, 0
	s_addc_u32 s8, s41, 0
	s_mov_b32 s9, -2
	s_waitcnt lgkmcnt(0)
	v_mov_b32_e32 v1, v0
	v_mov_b64_e32 v[2:3], 0
	v_mov_b64_e32 v[4:5], 0
	v_mov_b64_e32 v[6:7], 0
	v_mov_b64_e32 v[8:9], 0
	v_mov_b64_e32 v[10:11], 0
	v_mov_b64_e32 v[12:13], 0
	v_mov_b64_e32 v[14:15], 0
	v_mov_b64_e32 v[16:17], 0
	v_mov_b64_e32 v[18:19], 0
	v_mov_b64_e32 v[20:21], 0
	v_mov_b64_e32 v[22:23], 0
	v_mov_b64_e32 v[24:25], 0
	v_mov_b64_e32 v[26:27], 0
	v_mov_b64_e32 v[28:29], 0
	v_mov_b64_e32 v[30:31], 0
	v_mov_b64_e32 v[32:33], 0
	v_mov_b64_e32 v[34:35], 0
	v_mov_b64_e32 v[36:37], 0
	v_mov_b64_e32 v[38:39], 0
	v_mov_b64_e32 v[40:41], 0
	v_mov_b64_e32 v[42:43], 0
	v_mov_b64_e32 v[44:45], 0
	v_mov_b64_e32 v[46:47], 0
	v_mov_b64_e32 v[48:49], 0
	v_mov_b64_e32 v[50:51], 0
	v_mov_b64_e32 v[52:53], 0
	v_mov_b64_e32 v[54:55], 0
	v_mov_b64_e32 v[56:57], 0
	v_mov_b64_e32 v[58:59], 0
	v_mov_b64_e32 v[60:61], 0
	v_mov_b64_e32 v[62:63], 0
	v_mov_b64_e32 v[64:65], 0
	v_mov_b64_e32 v[66:67], 0
	v_mov_b64_e32 v[68:69], 0
	v_mov_b64_e32 v[70:71], 0
	v_mov_b64_e32 v[72:73], 0
	v_mov_b64_e32 v[74:75], 0
	v_mov_b64_e32 v[76:77], 0
	v_mov_b64_e32 v[78:79], 0
	v_mov_b64_e32 v[80:81], 0
	v_mov_b64_e32 v[82:83], 0
	v_mov_b64_e32 v[84:85], 0
	v_mov_b64_e32 v[86:87], 0
	v_mov_b64_e32 v[88:89], 0
	v_mov_b64_e32 v[90:91], 0
	v_mov_b64_e32 v[92:93], 0
	v_mov_b64_e32 v[94:95], 0
	v_mov_b64_e32 v[96:97], 0
	v_mov_b64_e32 v[98:99], 0
	v_mov_b64_e32 v[100:101], 0
	v_mov_b64_e32 v[102:103], 0
	v_mov_b64_e32 v[104:105], 0
	v_mov_b64_e32 v[106:107], 0
	v_mov_b64_e32 v[108:109], 0
	v_mov_b64_e32 v[110:111], 0
	v_mov_b64_e32 v[112:113], 0
	v_mov_b64_e32 v[114:115], 0
	v_mov_b64_e32 v[116:117], 0
	v_mov_b64_e32 v[118:119], 0
	v_mov_b64_e32 v[132:133], 0
	v_mov_b64_e32 v[134:135], 0
	v_mov_b64_e32 v[140:141], 0
	v_mov_b64_e32 v[142:143], 0
	s_cmp_lg_u32 s100, 1
	s_cbranch_scc1 .Ldefbar_skip_10
	s_mov_b32 s100, 0
	s_barrier
